# context-token DFT (layer 0): twiddles broadcast from an LDS table, VC rows loaded 8 at a time double-buffered instead of 256 serialized load round trips per thread; same arithmetic order
# speedup vs baseline: 1.0243x; 1.0243x over previous
; __device__ __forceinline__ void fft1_phase(KP P, int l) {
;     ...
;     if (l == 0) {
;         const unsigned* VC = (const unsigned*)(ws + WS_VC); bf16_t* OM = (bf16_t*)(ws + WS_XN);
;         for (int gt = bid_ * 512 + tid_; gt < NB * CTXL * 256; gt += gridDim.x * 512) {
;             const int ch = gt & 255, k = (gt >> 8) & 255, b = gt >> 16;
;             const unsigned* vp = VC + (size_t)(b * 256) * 256 + ch; float a = 0.f;
.Lf1_done:
.LBB0_43:
	s_add_i32 s2, s70, 10
	s_cmp_lt_u32 s2, 23
	s_movk_i32 s2, 0x600
	s_cbranch_scc0 .LBB0_50
	v_cmp_gt_u32_e32 vcc, 0x100, v146
	s_and_saveexec_b64 s[20:21], vcc
	v_lshlrev_b32_e32 v26, 7, v146
	v_add_u32_e32 v27, 0x6000, v26
	v_and_b32_e32 v27, 0x7fff, v27
	global_load_dword v28, v26, s[6:7]
	global_load_dword v29, v27, s[6:7]
	v_lshlrev_b32_e32 v30, 3, v146
	v_add_u32_e32 v30, 0x1e000, v30
	s_waitcnt vmcnt(0)
	ds_write_b64 v30, v[28:29]
	s_or_b64 exec, exec, s[20:21]
	s_waitcnt lgkmcnt(0)
	s_barrier
	v_lshl_add_u32 v8, s0, 9, v146
	v_cmp_gt_i32_e32 vcc, s97, v8
	s_and_saveexec_b64 s[12:13], vcc
	s_cbranch_execz .LBB0_49
	v_readlane_b32 s2, v254, 18
	v_readlane_b32 s3, v254, 19
	s_load_dwordx2 s[14:15], s[2:3], 0xb8
	s_load_dword s0, s[72:73], 0x0
	v_lshlrev_b32_sdwa v168, v222, v146 dst_sel:DWORD dst_unused:UNUSED_PAD src0_sel:DWORD src1_sel:BYTE_0
	v_mov_b32_e32 v2, 2
	s_mov_b64 s[2:3], 0x4200600
	s_waitcnt lgkmcnt(0)
	v_lshl_add_u64 v[0:1], s[14:15], 0, v[168:169]
	v_lshlrev_b32_sdwa v168, v2, v146 dst_sel:DWORD dst_unused:UNUSED_PAD src0_sel:DWORD src1_sel:BYTE_0
	v_lshl_add_u64 v[0:1], v[0:1], 0, s[2:3]
	s_lshl_b32 s0, s0, 9
	v_lshl_add_u64 v[2:3], s[14:15], 0, v[168:169]
	s_mov_b64 s[14:15], 0

; __device__ __forceinline__ void fft1_phase(KP P, int l) {
;     ...
;         for (int gt = bid_ * 512 + tid_; gt < NB * CTXL * 256; gt += gridDim.x * 512) {
;             const int ch = gt & 255, k = (gt >> 8) & 255, b = gt >> 16;
;             const unsigned* vp = VC + (size_t)(b * 256) * 256 + ch; float a = 0.f;
; #pragma unroll 8
;             for (int j = 0; j < 256; ++j) { const unsigned pk = vp[(size_t)j * 256]; const float vr = __uint_as_float(pk << 16), vi = __uint_as_float(pk & 0xffff0000u);
;                 const int ix = ((k * j) & 255) * 32; a += vr * TAB[TAB_COS + ix] + vi * TAB[TAB_COS + ((ix - 2048) & 8191)]; }
.LBB0_47:
	v_readfirstlane_b32 s20, v9
	v_add_co_u32_e32 v20, vcc, 0xb100000, v4
	s_and_b32 s20, s20, 0xff
	s_nop 1
	v_addc_co_u32_e32 v21, vcc, 0, v5, vcc
	s_lshl_b32 s20, s20, 3
	v_add_co_u32_e32 v22, vcc, 0x1000, v20
	s_mov_b32 s21, 0x1e000
	s_nop 1
	v_addc_co_u32_e32 v23, vcc, 0, v21, vcc
	s_mov_b32 s2, 16
	global_load_dword v32, v[20:21], off offset:0
	global_load_dword v33, v[20:21], off offset:1024
	global_load_dword v34, v[20:21], off offset:2048
	global_load_dword v35, v[20:21], off offset:3072
	global_load_dword v36, v[22:23], off offset:0
	global_load_dword v37, v[22:23], off offset:1024
	global_load_dword v38, v[22:23], off offset:2048
	global_load_dword v39, v[22:23], off offset:3072
	v_mov_b32_e32 v24, s21
	s_add_i32 s21, s21, s20
	ds_read_b64 v[48:49], v24
	s_and_b32 s21, s21, 0x7f8
	s_or_b32 s21, s21, 0x1e000
	v_mov_b32_e32 v24, s21
	s_add_i32 s21, s21, s20
	ds_read_b64 v[50:51], v24
	s_and_b32 s21, s21, 0x7f8
	s_or_b32 s21, s21, 0x1e000
	v_mov_b32_e32 v24, s21
	s_add_i32 s21, s21, s20
	ds_read_b64 v[52:53], v24
	s_and_b32 s21, s21, 0x7f8
	s_or_b32 s21, s21, 0x1e000
	v_mov_b32_e32 v24, s21
	s_add_i32 s21, s21, s20
	ds_read_b64 v[54:55], v24
	s_and_b32 s21, s21, 0x7f8
	s_or_b32 s21, s21, 0x1e000
	v_mov_b32_e32 v24, s21
	s_add_i32 s21, s21, s20
	ds_read_b64 v[56:57], v24
	s_and_b32 s21, s21, 0x7f8
	s_or_b32 s21, s21, 0x1e000
	v_mov_b32_e32 v24, s21
	s_add_i32 s21, s21, s20
	ds_read_b64 v[58:59], v24
	s_and_b32 s21, s21, 0x7f8
	s_or_b32 s21, s21, 0x1e000
	v_mov_b32_e32 v24, s21
	s_add_i32 s21, s21, s20
	ds_read_b64 v[60:61], v24
	s_and_b32 s21, s21, 0x7f8
	s_or_b32 s21, s21, 0x1e000
	v_mov_b32_e32 v24, s21
	s_add_i32 s21, s21, s20
	ds_read_b64 v[62:63], v24
	s_and_b32 s21, s21, 0x7f8
	s_or_b32 s21, s21, 0x1e000
	v_add_co_u32_e32 v20, vcc, 0x2000, v20
	s_nop 1
	v_addc_co_u32_e32 v21, vcc, 0, v21, vcc
	v_add_co_u32_e32 v22, vcc, 0x2000, v22
	s_nop 1
	v_addc_co_u32_e32 v23, vcc, 0, v23, vcc
; __device__ __forceinline__ bf16_t f2bf(float f) { unsigned u = __float_as_uint(f); return (bf16_t)((u + 0x7fffu + ((u >> 16) & 1u)) >> 16); }
; __device__ __forceinline__ void fft1_phase(KP P, int l) {
;     ...
; #pragma unroll 8
;             for (int j = 0; j < 256; ++j) { const unsigned pk = vp[(size_t)j * 256]; const float vr = __uint_as_float(pk << 16), vi = __uint_as_float(pk & 0xffff0000u);
;                 const int ix = ((k * j) & 255) * 32; a += vr * TAB[TAB_COS + ix] + vi * TAB[TAB_COS + ((ix - 2048) & 8191)]; }
;             OM[(size_t)(b * RPB + SEQ + k) * DM + 768 + ch] = f2bf(a * (1.f / 128.f));
.Lcd_loop:
	global_load_dword v40, v[20:21], off offset:0
	global_load_dword v41, v[20:21], off offset:1024
	global_load_dword v42, v[20:21], off offset:2048
	global_load_dword v43, v[20:21], off offset:3072
	global_load_dword v44, v[22:23], off offset:0
	global_load_dword v45, v[22:23], off offset:1024
	global_load_dword v46, v[22:23], off offset:2048
	global_load_dword v47, v[22:23], off offset:3072
	v_mov_b32_e32 v24, s21
	s_add_i32 s21, s21, s20
	ds_read_b64 v[64:65], v24
	s_and_b32 s21, s21, 0x7f8
	s_or_b32 s21, s21, 0x1e000
	v_mov_b32_e32 v24, s21
	s_add_i32 s21, s21, s20
	ds_read_b64 v[66:67], v24
	s_and_b32 s21, s21, 0x7f8
	s_or_b32 s21, s21, 0x1e000
	v_mov_b32_e32 v24, s21
	s_add_i32 s21, s21, s20
	ds_read_b64 v[68:69], v24
	s_and_b32 s21, s21, 0x7f8
	s_or_b32 s21, s21, 0x1e000
	v_mov_b32_e32 v24, s21
	s_add_i32 s21, s21, s20
	ds_read_b64 v[70:71], v24
	s_and_b32 s21, s21, 0x7f8
	s_or_b32 s21, s21, 0x1e000
	v_mov_b32_e32 v24, s21
	s_add_i32 s21, s21, s20
	ds_read_b64 v[72:73], v24
	s_and_b32 s21, s21, 0x7f8
	s_or_b32 s21, s21, 0x1e000
	v_mov_b32_e32 v24, s21
	s_add_i32 s21, s21, s20
	ds_read_b64 v[74:75], v24
	s_and_b32 s21, s21, 0x7f8
	s_or_b32 s21, s21, 0x1e000
	v_mov_b32_e32 v24, s21
	s_add_i32 s21, s21, s20
	ds_read_b64 v[76:77], v24
	s_and_b32 s21, s21, 0x7f8
	s_or_b32 s21, s21, 0x1e000
	v_mov_b32_e32 v24, s21
	s_add_i32 s21, s21, s20
	ds_read_b64 v[78:79], v24
	s_and_b32 s21, s21, 0x7f8
	s_or_b32 s21, s21, 0x1e000
	v_add_co_u32_e32 v20, vcc, 0x2000, v20
	s_nop 1
	v_addc_co_u32_e32 v21, vcc, 0, v21, vcc
	v_add_co_u32_e32 v22, vcc, 0x2000, v22
	s_nop 1
	v_addc_co_u32_e32 v23, vcc, 0, v23, vcc
	s_waitcnt vmcnt(8) lgkmcnt(8)
	v_lshlrev_b32_e32 v26, 16, v32
	v_and_b32_e32 v27, 0xffff0000, v32
	v_pk_mul_f32 v[26:27], v[48:49], v[26:27]
	s_nop 0
	v_add_f32_e32 v26, v26, v27
	v_add_f32_e32 v19, v19, v26
	v_lshlrev_b32_e32 v26, 16, v33
	v_and_b32_e32 v27, 0xffff0000, v33
	v_pk_mul_f32 v[26:27], v[50:51], v[26:27]
	s_nop 0
	v_add_f32_e32 v26, v26, v27
	v_add_f32_e32 v19, v19, v26
	v_lshlrev_b32_e32 v26, 16, v34
	v_and_b32_e32 v27, 0xffff0000, v34
	v_pk_mul_f32 v[26:27], v[52:53], v[26:27]
	s_nop 0
	v_add_f32_e32 v26, v26, v27
	v_add_f32_e32 v19, v19, v26
	v_lshlrev_b32_e32 v26, 16, v35
	v_and_b32_e32 v27, 0xffff0000, v35
	v_pk_mul_f32 v[26:27], v[54:55], v[26:27]
	s_nop 0
	v_add_f32_e32 v26, v26, v27
	v_add_f32_e32 v19, v19, v26
	v_lshlrev_b32_e32 v26, 16, v36
	v_and_b32_e32 v27, 0xffff0000, v36
	v_pk_mul_f32 v[26:27], v[56:57], v[26:27]
	s_nop 0
	v_add_f32_e32 v26, v26, v27
	v_add_f32_e32 v19, v19, v26
	v_lshlrev_b32_e32 v26, 16, v37
	v_and_b32_e32 v27, 0xffff0000, v37
	v_pk_mul_f32 v[26:27], v[58:59], v[26:27]
	s_nop 0
	v_add_f32_e32 v26, v26, v27
	v_add_f32_e32 v19, v19, v26
	v_lshlrev_b32_e32 v26, 16, v38
	v_and_b32_e32 v27, 0xffff0000, v38
	v_pk_mul_f32 v[26:27], v[60:61], v[26:27]
	s_nop 0
	v_add_f32_e32 v26, v26, v27
	v_add_f32_e32 v19, v19, v26
	v_lshlrev_b32_e32 v26, 16, v39
	v_and_b32_e32 v27, 0xffff0000, v39
	v_pk_mul_f32 v[26:27], v[62:63], v[26:27]
	s_nop 0
	v_add_f32_e32 v26, v26, v27
	v_add_f32_e32 v19, v19, v26
	global_load_dword v32, v[20:21], off offset:0
	global_load_dword v33, v[20:21], off offset:1024
	global_load_dword v34, v[20:21], off offset:2048
	global_load_dword v35, v[20:21], off offset:3072
	global_load_dword v36, v[22:23], off offset:0
	global_load_dword v37, v[22:23], off offset:1024
	global_load_dword v38, v[22:23], off offset:2048
	global_load_dword v39, v[22:23], off offset:3072
	v_mov_b32_e32 v24, s21
	s_add_i32 s21, s21, s20
	ds_read_b64 v[48:49], v24
	s_and_b32 s21, s21, 0x7f8
	s_or_b32 s21, s21, 0x1e000
	v_mov_b32_e32 v24, s21
	s_add_i32 s21, s21, s20
	ds_read_b64 v[50:51], v24
	s_and_b32 s21, s21, 0x7f8
	s_or_b32 s21, s21, 0x1e000
	v_mov_b32_e32 v24, s21
	s_add_i32 s21, s21, s20
	ds_read_b64 v[52:53], v24
	s_and_b32 s21, s21, 0x7f8
	s_or_b32 s21, s21, 0x1e000
	v_mov_b32_e32 v24, s21
	s_add_i32 s21, s21, s20
	ds_read_b64 v[54:55], v24
	s_and_b32 s21, s21, 0x7f8
	s_or_b32 s21, s21, 0x1e000
	v_mov_b32_e32 v24, s21
	s_add_i32 s21, s21, s20
	ds_read_b64 v[56:57], v24
	s_and_b32 s21, s21, 0x7f8
	s_or_b32 s21, s21, 0x1e000
	v_mov_b32_e32 v24, s21
	s_add_i32 s21, s21, s20
	ds_read_b64 v[58:59], v24
	s_and_b32 s21, s21, 0x7f8
	s_or_b32 s21, s21, 0x1e000
	v_mov_b32_e32 v24, s21
	s_add_i32 s21, s21, s20
	ds_read_b64 v[60:61], v24
	s_and_b32 s21, s21, 0x7f8
	s_or_b32 s21, s21, 0x1e000
	v_mov_b32_e32 v24, s21
	s_add_i32 s21, s21, s20
	ds_read_b64 v[62:63], v24
	s_and_b32 s21, s21, 0x7f8
	s_or_b32 s21, s21, 0x1e000
	v_add_co_u32_e32 v20, vcc, 0x2000, v20
	s_nop 1
	v_addc_co_u32_e32 v21, vcc, 0, v21, vcc
	v_add_co_u32_e32 v22, vcc, 0x2000, v22
	s_nop 1
	v_addc_co_u32_e32 v23, vcc, 0, v23, vcc
	s_waitcnt vmcnt(8) lgkmcnt(8)
	v_lshlrev_b32_e32 v26, 16, v40
	v_and_b32_e32 v27, 0xffff0000, v40
	v_pk_mul_f32 v[26:27], v[64:65], v[26:27]
	s_nop 0
	v_add_f32_e32 v26, v26, v27
	v_add_f32_e32 v19, v19, v26
	v_lshlrev_b32_e32 v26, 16, v41
	v_and_b32_e32 v27, 0xffff0000, v41
	v_pk_mul_f32 v[26:27], v[66:67], v[26:27]
	s_nop 0
	v_add_f32_e32 v26, v26, v27
	v_add_f32_e32 v19, v19, v26
	v_lshlrev_b32_e32 v26, 16, v42
	v_and_b32_e32 v27, 0xffff0000, v42
	v_pk_mul_f32 v[26:27], v[68:69], v[26:27]
	s_nop 0
	v_add_f32_e32 v26, v26, v27
	v_add_f32_e32 v19, v19, v26
	v_lshlrev_b32_e32 v26, 16, v43
	v_and_b32_e32 v27, 0xffff0000, v43
	v_pk_mul_f32 v[26:27], v[70:71], v[26:27]
	s_nop 0
	v_add_f32_e32 v26, v26, v27
	v_add_f32_e32 v19, v19, v26
	v_lshlrev_b32_e32 v26, 16, v44
	v_and_b32_e32 v27, 0xffff0000, v44
	v_pk_mul_f32 v[26:27], v[72:73], v[26:27]
	s_nop 0
	v_add_f32_e32 v26, v26, v27
	v_add_f32_e32 v19, v19, v26
	v_lshlrev_b32_e32 v26, 16, v45
	v_and_b32_e32 v27, 0xffff0000, v45
	v_pk_mul_f32 v[26:27], v[74:75], v[26:27]
	s_nop 0
	v_add_f32_e32 v26, v26, v27
	v_add_f32_e32 v19, v19, v26
	v_lshlrev_b32_e32 v26, 16, v46
	v_and_b32_e32 v27, 0xffff0000, v46
	v_pk_mul_f32 v[26:27], v[76:77], v[26:27]
	s_nop 0
	v_add_f32_e32 v26, v26, v27
	v_add_f32_e32 v19, v19, v26
	v_lshlrev_b32_e32 v26, 16, v47
	v_and_b32_e32 v27, 0xffff0000, v47
	v_pk_mul_f32 v[26:27], v[78:79], v[26:27]
	s_nop 0
	v_add_f32_e32 v26, v26, v27
	v_add_f32_e32 v19, v19, v26
	s_sub_u32 s2, s2, 1
	s_cmp_lg_u32 s2, 0
	s_cbranch_scc1 .Lcd_loop
	s_waitcnt vmcnt(0) lgkmcnt(0)
	v_mul_f32_e32 v4, 0x3c000000, v19
	v_bfe_u32 v5, v4, 16, 1
	v_add3_u32 v6, v4, v5, s44
	v_mul_i32_i24_sdwa v4, sext(v8), s81 dst_sel:DWORD dst_unused:UNUSED_PAD src0_sel:WORD_1 src1_sel:DWORD
	v_and_or_b32 v4, v9, s36, v4
	v_add_u32_e32 v4, 0x2000, v4
	v_ashrrev_i32_e32 v5, 31, v4
	v_add_u32_e32 v8, s0, v8
	s_mov_b32 s2, 0x1ffff
	v_lshlrev_b64 v[4:5], 11, v[4:5]
	v_cmp_lt_i32_e32 vcc, s2, v8
	v_lshl_add_u64 v[4:5], v[0:1], 0, v[4:5]
	s_or_b64 s[14:15], vcc, s[14:15]
	global_store_short_d16_hi v[4:5], v6, off
	s_andn2_b64 exec, exec, s[14:15]
	s_cbranch_execnz .LBB0_46
